# v21 + P5->P6 grid barrier replaced by 8-workgroup row-panel barrier (same-XCD verified at run time, no L2 flush)
# speedup vs baseline: 1.0049x; 1.0049x over previous
; #define LAS __attribute__((address_space(3)))
; __device__ __forceinline__ unsigned xb_add(unsigned* p, unsigned v) { return __hip_atomic_fetch_add(p, v, __ATOMIC_RELAXED, __HIP_MEMORY_SCOPE_AGENT); }
; __device__ __forceinline__ unsigned xb_xcc_id() { return (unsigned)__builtin_amdgcn_s_getreg((3 << 11) | 20) & 0xFu; }
; __device__ __forceinline__ XcdBarrier xcd_barrier_post(unsigned* bar, volatile LAS unsigned* st) {
;     XcdBarrier b; b.bar = bar; b.x = xb_xcc_id(); b.st = st;
;     if (threadIdx.x == 0) (void)xb_add(&bar[XB_XCNT(b.x)], 1u);
;     return b;
; }
; __global__ void __launch_bounds__(NWAVES * 64, 2) mega_fwd(Args args) {
;     ...
;     for (int u = F.tid; u < (LDS_BYTES - LDSCTL_OFF) / 4; u += NWAVES * 64) ((LAS unsigned*)(F.lds + LDSCTL_OFF))[u] = 0u;
;     __syncthreads();
;     const int lo = args.ph_lo, hi = args.ph_hi;
;     XcdBarrier bar; bar.bar = (unsigned*)(ws + WS_CTL) + CW_BAR; bar.x = 0; bar.st = nullptr;
;     if (hi - lo > 1 || DUP_MASK) bar = xcd_barrier_post((unsigned*)(ws + WS_CTL) + CW_BAR, (volatile LAS unsigned*)(F.lds + MISC_OFF) + 8);
.LBB0_2:
	v_lshl_add_u32 v158, v0, 2, 0
	v_add_u32_e32 v1, 0x20000, v158
	v_mov_b32_e32 v2, 0
	ds_write2st64_b32 v1, v2, v2 offset1:8
	ds_write2st64_b32 v1, v2, v2 offset0:16 offset1:24
	v_or_b32_e32 v1, 0x800, v0
	s_mov_b64 s[2:3], -1
	s_and_saveexec_b64 s[4:5], s[2:3]
	v_lshl_add_u32 v3, v1, 2, 0
	v_add_u32_e32 v3, 0x20000, v3
	ds_write_b32 v3, v2
	s_or_b64 exec, exec, s[4:5]
	s_and_saveexec_b64 s[4:5], s[2:3]
	s_add_i32 s2, 0, 0x20000
	v_lshl_add_u32 v1, v1, 2, s2
	v_mov_b32_e32 v2, 0
	ds_write_b32 v1, v2 offset:2048
	s_or_b64 exec, exec, s[4:5]
	s_load_dwordx2 s[8:9], s[0:1], 0x80
	v_or_b32_e32 v1, 0xc00, v0
	v_cmp_gt_u32_e64 s[2:3], 7, 6
	v_cmp_gt_u32_e64 s[6:7], 7, 5
	s_and_saveexec_b64 s[4:5], s[6:7]
	v_lshl_add_u32 v2, v1, 2, 0
	v_add_u32_e32 v2, 0x20000, v2
	v_mov_b32_e32 v3, 0
	ds_write_b32 v2, v3
	s_waitcnt lgkmcnt(0)
	v_writelane_b32 v255, s8, 5
	s_nop 1
	v_writelane_b32 v255, s9, 6
	s_or_b64 exec, exec, s[4:5]
	s_load_dwordx16 s[12:27], s[0:1], 0x40
	s_and_saveexec_b64 s[4:5], s[2:3]
	s_add_i32 s2, 0, 0x20000
	v_lshl_add_u32 v1, v1, 2, s2
	v_mov_b32_e32 v2, 0
	ds_write_b32 v1, v2 offset:2048
	s_or_b64 exec, exec, s[4:5]
	s_load_dwordx16 s[36:51], s[0:1], 0x0
	v_readlane_b32 s0, v255, 5
	s_waitcnt lgkmcnt(0)
	s_add_u32 s76, s26, 0x4000
	v_readlane_b32 s1, v255, 6
	s_addc_u32 s77, s27, 0
	s_sub_i32 s0, s1, s0
	s_mov_b32 s1, 0
	v_writelane_b32 v255, s1, 7
	s_cmp_lt_i32 s0, 2
	s_mov_b32 s0, 0
	s_barrier
	s_cbranch_scc1 .LBB0_15
	s_getreg_b32 s0, hwreg(HW_REG_XCC_ID, 0, 4)
	s_and_b32 s0, s0, 15
	v_writelane_b32 v255, s0, 7
	v_cmp_eq_u32_e32 vcc, 0, v0
	s_and_saveexec_b64 s[0:1], vcc
	s_cbranch_execz .LBB0_14
	s_mov_b64 s[2:3], exec
	v_mbcnt_lo_u32_b32 v1, s2, 0
	v_mbcnt_hi_u32_b32 v1, s3, v1
	v_cmp_eq_u32_e32 vcc, 0, v1
	s_and_b64 s[4:5], exec, vcc
	s_mov_b64 exec, s[4:5]
	s_cbranch_execz .LBB0_14
	v_readlane_b32 s4, v255, 7
	s_lshl_b32 s4, s4, 8
	s_bcnt1_i32_b64 s2, s[2:3]
	v_mov_b32_e32 v1, s4
	v_mov_b32_e32 v2, s2
	global_atomic_add v1, v2, s[76:77] offset:1024
	v_readlane_b32 s5, v255, 7
	s_add_i32 s5, s5, 1
	v_readlane_b32 s6, v255, 2
	s_and_b32 s7, s6, 7
	s_lshr_b32 s6, s6, 3
	s_lshl_b32 s7, s7, 5
	s_and_b32 s8, s6, 3
	s_lshl_b32 s8, s8, 3
	s_add_i32 s7, s7, s8
	s_lshr_b32 s6, s6, 2
	s_add_i32 s7, s7, s6
	s_lshl_b32 s7, s7, 2
	s_add_i32 s7, s7, 0x51000
	v_mov_b32_e32 v6, s7
	v_mov_b32_e32 v10, s5
	global_store_dword v6, v10, s[26:27] sc1

; #define PHASE(k, ...) do { if (lo <= (k) && (k) < hi) { __VA_ARGS__ if (DUP(k)) { xcd_barrier(bar); __VA_ARGS__ } if ((k) + 1 < hi) xcd_barrier(bar); if ((k) == TS_PHASE) tsk_ = __builtin_amdgcn_s_memrealtime() - ts0_; } } while (0)
; __global__ void __launch_bounds__(NWAVES * 64, 2) mega_fwd(Args args) {
;     ...
;     PHASE(5, {
;         pg8::Gemm g{(const bf16_t*)(ws + WS_Y), (const bf16_t*)(ws + WS_W2T), YLD, YLD}; MergeOrder S; S.so.init(MTOK / 256, DM / 256, 0, F.G, (int)blockIdx.x);
;         if (EPI_PROBE == 3) { pg8::EpiMerge E0{(const bf16_t*)(ws + WS_GATES), (bf16_t*)(ws + WS_MERGED), 1, 0}; pg8::gemm_phase<pg8::EpiMerge, MergeOrder, false>(F.lds + RING_OFF, g, S, E0); xcd_barrier(bar); }
;         pg8::EpiMerge E{(const bf16_t*)(ws + WS_GATES), (bf16_t*)(ws + WS_MERGED), 0, 0};
;         pg8::gemm_phase<pg8::EpiMerge, MergeOrder, true>(F.lds + RING_OFF, g, S, E); });
;     PHASE(6, {
.LBB0_947:
	v_readlane_b32 s0, v255, 9
	s_cmp_eq_u32 s0, 0
	s_cbranch_scc1 .Lgb_nold
	v_readfirstlane_b32 s0, v0
	s_cmp_ge_u32 s0, 64
	s_cbranch_scc1 .Lgb_nold
	v_readlane_b32 s0, v255, 2
	s_and_b32 s1, s0, 7
	s_lshr_b32 s0, s0, 3
	s_and_b32 s0, s0, 3
	s_lshl_b32 s1, s1, 2
	s_add_i32 s0, s0, s1
	s_lshl_b32 s0, s0, 5
	s_add_i32 s0, s0, 0x51000
	v_and_b32_e32 v1, 7, v0
	v_lshl_add_u32 v1, v1, 2, s0
	global_load_dword v1, v1, s[26:27] sc1

; __device__ __forceinline__ unsigned xb_ld(unsigned* p)              { return __hip_atomic_load(p, __ATOMIC_RELAXED, __HIP_MEMORY_SCOPE_AGENT); }
; __device__ __forceinline__ unsigned xb_add(unsigned* p, unsigned v) { return __hip_atomic_fetch_add(p, v, __ATOMIC_RELAXED, __HIP_MEMORY_SCOPE_AGENT); }
; #define XB_SPIN(cond, bar) do { unsigned _sp = 0; while (cond) { __builtin_amdgcn_s_sleep(1); \
;     if ((++_sp & 255u) == 0u) { if (xb_ld(&(bar)[XB_TMO])) break; if (_sp > XB_SPIN_CAP) { atomicAdd(&(bar)[XB_TMO], 1u); break; } } } } while (0)
; __device__ __forceinline__ void xcd_barrier(const XcdBarrier& b) {
;     asm volatile("s_waitcnt vmcnt(0)" ::: "memory");
;     __syncthreads();
;     if (threadIdx.x == 0) {
;         unsigned* bar = b.bar;
;         __builtin_amdgcn_s_waitcnt(0);
;         unsigned nloc = b.st[0], nx = b.st[1];
;         if (nloc == 0u) { xcd_barrier_complete(bar, b.x, nloc, nx); b.st[0] = nloc; b.st[1] = nx; }
;         const unsigned old = xb_add(&bar[XB_XSUB(b.x)], 1u);
;         const unsigned gen = old / nloc;
;         if (old + 1u == (gen + 1u) * nloc) {
;             __builtin_amdgcn_fence(__ATOMIC_RELEASE, "agent");
;             asm volatile("s_waitcnt vmcnt(0)" ::: "memory");
;             const unsigned og = xb_add(&bar[XB_TOP], 1u);
;             const unsigned tg = og / nx;
;             if (og + 1u == (tg + 1u) * nx) xb_add(&bar[XB_TOPGEN], 1u);
;             else XB_SPIN(xb_ld(&bar[XB_TOPGEN]) == tg, bar);
;             __builtin_amdgcn_fence(__ATOMIC_ACQUIRE, "agent");
;             xb_add(&bar[XB_XGEN(b.x)], 1u);
;             asm volatile("s_waitcnt vmcnt(0)" ::: "memory");
;         } else {
;             XB_SPIN(xb_ld(&bar[XB_XGEN(b.x)]) == gen, bar);
;             __builtin_amdgcn_fence(__ATOMIC_ACQUIRE, "agent");
;             asm volatile("s_waitcnt vmcnt(0)" ::: "memory");
;         }
;     }
;     __syncthreads();
; }
.LBB0_948:
	v_readlane_b32 s4, v255, 5
	v_readlane_b32 s5, v255, 6
	s_cmp_lt_i32 s5, 7
	s_cbranch_scc1 .LBB0_998
	v_readlane_b32 s0, v255, 9
	s_cmp_eq_u32 s0, 0
	s_cbranch_scc1 .Lgb_grid
	s_waitcnt vmcnt(0)
	s_barrier
	v_readlane_b32 s4, v1, 0
	v_cmp_ne_u32_e32 vcc, s4, v1
	s_and_b32 s5, vcc_lo, 0xff
	s_cmp_eq_u32 s5, 0
	s_cselect_b32 s5, 1, 0
	s_cmp_lg_u32 s4, 0
	s_cselect_b32 s98, s5, 0
	v_cmp_eq_u32_e32 vcc, 0, v0
	s_and_saveexec_b64 s[2:3], vcc
	s_cbranch_execz .LBB0_997
	s_cmp_eq_u32 s98, 1
	s_cbranch_scc1 .Lgb_noflush
	buffer_wbl2 sc1
	s_waitcnt vmcnt(0)
.Lgb_noflush:
	v_readlane_b32 s0, v255, 2
	s_and_b32 s1, s0, 7
	s_lshr_b32 s0, s0, 3
	s_and_b32 s0, s0, 3
	s_lshl_b32 s1, s1, 2
	s_add_i32 s0, s0, s1
	s_lshl_b32 s0, s0, 8
	s_add_i32 s0, s0, 0x50000
	s_add_u32 s4, s26, s0
	s_addc_u32 s5, s27, 0
	v_mov_b32_e32 v1, 0
	v_mov_b32_e32 v2, 1
	global_atomic_add v1, v2, s[4:5]
	s_mov_b32 s6, 0
.Lgb_spin:
	global_load_dword v3, v1, s[4:5] sc1
	s_waitcnt vmcnt(0)
	v_readfirstlane_b32 s7, v3
	s_cmp_ge_u32 s7, 8
	s_cbranch_scc1 .Lgb_done
	s_sleep 1
	s_add_i32 s6, s6, 1
	s_cmp_lt_u32 s6, 0x4000
	s_cbranch_scc1 .Lgb_spin
.Lgb_done:
	buffer_inv sc1
	s_waitcnt vmcnt(0)
	s_branch .LBB0_997
.Lgb_grid:
	s_waitcnt vmcnt(0)
	v_cmp_eq_u32_e32 vcc, 0, v0
	s_waitcnt vmcnt(0)
	s_barrier
	s_and_saveexec_b64 s[2:3], vcc
	s_cbranch_execz .LBB0_997
	v_readlane_b32 s0, v255, 8
	s_waitcnt vmcnt(0) expcnt(0) lgkmcnt(0)
	s_nop 0
	v_mov_b32_e32 v1, s0
	ds_read_b32 v3, v1
	ds_read_b32 v1, v1 offset:4
	s_waitcnt lgkmcnt(1)
	v_cmp_ne_u32_e32 vcc, 0, v3
	s_cbranch_vccnz .LBB0_965
	v_readlane_b32 s4, v255, 0
	v_readlane_b32 s5, v255, 1
	s_load_dwordx2 s[0:1], s[4:5], 0x4
	s_add_u32 s4, s26, 0x4200
	s_addc_u32 s5, s27, 0
	s_add_u32 s6, s26, 0x4400
	s_addc_u32 s7, s27, 0
	s_add_u32 s8, s26, 0x4500
	s_addc_u32 s9, s27, 0
	s_add_u32 s12, s26, 0x4600
	s_addc_u32 s13, s27, 0
	s_add_u32 s14, s26, 0x4700
	s_addc_u32 s15, s27, 0
	s_add_u32 s16, s26, 0x4800
	s_addc_u32 s17, s27, 0
	s_add_u32 s18, s26, 0x4900
	s_addc_u32 s19, s27, 0
	s_add_u32 s20, s26, 0x4a00
	s_addc_u32 s21, s27, 0
	s_add_u32 s28, s26, 0x4b00
	s_addc_u32 s29, s27, 0
	s_add_u32 s30, s26, 0x4c00
	s_addc_u32 s31, s27, 0
	s_add_u32 s38, s26, 0x4d00
	s_addc_u32 s39, s27, 0
	s_add_u32 s40, s26, 0x4e00
	s_addc_u32 s41, s27, 0
	s_add_u32 s42, s26, 0x4f00
	s_addc_u32 s43, s27, 0
	s_add_u32 s44, s26, 0x5000
	s_addc_u32 s45, s27, 0
	s_add_u32 s46, s26, 0x5100
	s_addc_u32 s47, s27, 0
	s_add_u32 s48, s26, 0x5200
	s_addc_u32 s49, s27, 0
	s_waitcnt lgkmcnt(0)
	s_mul_i32 s0, s0, s52
	s_add_u32 s50, s26, 0x5300
	s_mul_i32 s0, s0, s1
	s_addc_u32 s51, s27, 0
	s_mov_b32 s1, 1
	v_mov_b32_e32 v17, 0
	s_branch .LBB0_953
